# strategy 4: one static s_setprio 1 for waves 4-7 over each GEMM phase, per-phase flips deleted
# baseline (speedup 1.0000x reference)
.LBB0_223:
	s_or_b64 exec, exec, s[0:1]
	s_cmpk_lt_i32 s2, 0x100
	s_waitcnt lgkmcnt(0)
	v_mov_b32_e32 v0, v224
	s_mul_i32 s34, s26, 48
	s_barrier
	s_cselect_b32 s99, 1, 0
	v_readfirstlane_b32 s98, v224
	s_lshr_b32 s98, s98, 8
	s_cbranch_scc0 .Lgp_skip0
	s_setprio 1
.Lgp_skip0:
	s_cmp_lg_u32 s99, 0
	s_cbranch_scc0 .LBB0_231
	s_waitcnt vmcnt(7)
	v_ashrrev_i32_e32 v36, 8, v0
	v_and_b32_e32 v1, 0xff, v0
	v_lshl_or_b32 v4, v36, 12, v1
	v_mov_b32_e32 v2, s60
	v_mov_b32_e32 v3, s61
	v_ashrrev_i32_e32 v5, 31, v4
	v_lshl_add_u64 v[12:13], v[4:5], 2, v[2:3]
	s_movk_i32 s0, 0x1000
	v_add_co_u32_e32 v14, vcc, s0, v12
	s_movk_i32 s0, 0x2000
	s_nop 0
	v_addc_co_u32_e32 v15, vcc, 0, v13, vcc
	v_add_co_u32_e32 v8, vcc, s0, v12
	s_movk_i32 s0, 0x3000
	s_nop 0
	v_addc_co_u32_e32 v9, vcc, 0, v13, vcc
	v_add_co_u32_e32 v20, vcc, s0, v12
	global_load_dword v2, v[8:9], off offset:-4096
	global_load_dword v4, v[8:9], off
	global_load_dword v5, v[8:9], off offset:1024
	global_load_dword v6, v[8:9], off offset:2048
	global_load_dword v7, v[8:9], off offset:3072
	v_addc_co_u32_e32 v21, vcc, 0, v13, vcc
	global_load_dword v8, v[12:13], off
	global_load_dword v9, v[12:13], off offset:1024
	global_load_dword v10, v[12:13], off offset:2048
	global_load_dword v11, v[12:13], off offset:3072
	global_load_dword v3, v[14:15], off offset:1024
	s_nop 0
	global_load_dword v12, v[14:15], off offset:2048
	global_load_dword v13, v[14:15], off offset:3072
	s_nop 0
	global_load_dword v14, v[20:21], off
	global_load_dword v15, v[20:21], off offset:1024
	global_load_dword v16, v[20:21], off offset:2048
	global_load_dword v17, v[20:21], off offset:3072
	v_mov_b32_e32 v18, s62
	v_mov_b32_e32 v19, s63
	v_ashrrev_i32_e32 v1, 31, v0
	v_lshl_add_u64 v[18:19], v[0:1], 2, v[18:19]
	global_load_dword v33, v[18:19], off
	v_ashrrev_i32_e32 v37, 6, v0
	s_waitcnt vmcnt(23)
	v_and_b32_e32 v34, 15, v0
	v_lshlrev_b32_e32 v18, 7, v37
	v_mov_b32_e32 v23, 0
	v_ashrrev_i32_e32 v19, 31, v18
	s_waitcnt vmcnt(21)
	v_lshlrev_b32_e32 v24, 11, v34
	v_mov_b32_e32 v25, v23
	v_bfe_u32 v32, v0, 4, 2
	v_lshlrev_b64 v[20:21], 1, v[18:19]
	v_lshl_add_u64 v[24:25], s[24:25], 0, v[24:25]
	v_lshl_add_u64 v[18:19], s[30:31], 0, v[20:21]
	v_lshlrev_b32_e32 v22, 4, v32
	v_lshl_add_u64 v[20:21], v[24:25], 0, v[20:21]
	v_lshl_add_u64 v[24:25], v[0:1], 1, s[24:25]
	s_mov_b64 s[4:5], 0x7522000
	v_mul_lo_u32 v1, v37, 48
	v_lshl_add_u64 v[30:31], v[20:21], 0, v[22:23]
	s_mov_b64 s[0:1], 0x800000
	v_lshl_add_u64 v[24:25], v[24:25], 0, s[4:5]
	s_mov_b64 s[4:5], 0x808040
	v_lshl_or_b32 v1, v32, 2, v1
	s_movk_i32 s3, 0x84
	v_lshl_add_u64 v[20:21], v[30:31], 0, s[0:1]
	s_mov_b64 s[0:1], 0x808000
	v_lshl_add_u64 v[26:27], v[30:31], 0, s[4:5]
	s_mov_b64 s[4:5], 0x808080
	v_mul_lo_u32 v1, v1, s3
	v_lshl_add_u64 v[18:19], v[18:19], 0, v[22:23]
	v_lshl_add_u64 v[22:23], v[30:31], 0, s[0:1]
	v_lshl_add_u32 v35, v34, 2, 0
	s_movk_i32 s0, 0x600
	v_and_b32_e32 v38, 31, v0
	v_lshl_add_u64 v[28:29], v[30:31], 0, s[4:5]
	s_mov_b64 s[4:5], 0x8080c0
	v_add_u32_e32 v37, 0x840, v1
	v_add_u32_e32 v39, 0x1080, v1
	v_lshl_add_u32 v36, v36, 6, 0
	v_cmp_gt_i32_e64 s[0:1], s0, v0
	v_lshl_add_u64 v[30:31], v[30:31], 0, s[4:5]
	v_lshl_add_u32 v32, v38, 2, 0
	s_mul_i32 s10, s2, 48
	v_add_u32_e32 v36, 0xc600, v36
	v_add_u32_e32 v37, v35, v37
	v_add_u32_e32 v38, v35, v39
	s_movk_i32 s11, 0x90
	s_movk_i32 s12, 0x3ff
	s_mov_b32 s13, 0xbfb8aa3b
	s_mov_b32 s14, 0x800000
	s_mov_b32 s15, 0x3f317217
	s_mov_b32 s16, 0x7f800000
	s_mov_b32 s17, 0x3d800000
	v_mov_b32_e32 v39, 0x41b17218
	s_mov_b32 s19, s2

.LBB0_761:
	s_setprio 0
	s_waitcnt vmcnt(0)
	s_waitcnt vmcnt(0) lgkmcnt(0)
	s_barrier
	s_mov_b64 s[0:1], exec
	v_readlane_b32 s4, v254, 9
	v_readlane_b32 s5, v254, 10
	s_and_b64 s[4:5], s[0:1], s[4:5]
	s_xor_b64 s[0:1], s[4:5], s[0:1]
	s_mov_b64 exec, s[4:5]
	s_cbranch_execz .LBB0_814
	s_add_i32 s3, 0, 0x20000
	v_mov_b32_e32 v0, s3
	s_waitcnt vmcnt(0) expcnt(0) lgkmcnt(0)
	ds_read_b32 v2, v0
	s_add_i32 s3, 0, 0x20004
	v_mov_b32_e32 v0, s3
	ds_read_b32 v0, v0
	s_waitcnt lgkmcnt(1)
	v_cmp_ne_u32_e32 vcc, 0, v2
	s_cbranch_vccnz .LBB0_777
	s_add_u32 s4, s24, 0xed22200
	s_addc_u32 s5, s25, 0
	s_add_u32 s6, s24, 0xed22400
	s_addc_u32 s7, s25, 0
	s_add_u32 s8, s24, 0xed22500
	s_addc_u32 s9, s25, 0
	s_add_u32 s10, s24, 0xed22600
	s_addc_u32 s11, s25, 0
	s_add_u32 s12, s24, 0xed22700
	s_addc_u32 s13, s25, 0
	s_add_u32 s14, s24, 0xed22800
	s_addc_u32 s15, s25, 0
	s_add_u32 s56, s24, 0xed22900
	s_addc_u32 s57, s25, 0
	s_add_u32 s58, s24, 0xed22a00
	s_addc_u32 s59, s25, 0
	s_add_u32 s62, s24, 0xed22b00
	s_addc_u32 s63, s25, 0
	s_add_u32 s80, s24, 0xed22c00
	s_addc_u32 s81, s25, 0
	s_add_u32 s82, s24, 0xed22d00
	s_addc_u32 s83, s25, 0
	s_add_u32 s86, s24, 0xed22e00
	s_addc_u32 s87, s25, 0
	s_add_u32 s88, s24, 0xed22f00
	s_addc_u32 s89, s25, 0
	s_add_u32 s90, s24, 0xed23000
	s_addc_u32 s91, s25, 0
	s_add_u32 s92, s24, 0xed23100
	s_addc_u32 s93, s25, 0
	s_add_u32 s94, s24, 0xed23200
	v_readlane_b32 s3, v254, 8
	s_addc_u32 s95, s25, 0
	s_mul_i32 s3, s27, s3
	s_add_u32 s96, s24, 0xed23300
	s_mul_i32 s3, s3, s26
	s_addc_u32 s97, s25, 0
	s_mov_b32 s19, 1
	v_mov_b32_e32 v16, 0
	s_branch .LBB0_765

.LBB0_1059:
	s_or_b64 exec, exec, s[0:1]
	s_add_u32 s10, s24, 0xa522000
	s_addc_u32 s11, s25, 0
	s_cmpk_lt_i32 s2, 0xc0
	s_cselect_b64 s[12:13], -1, 0
	s_waitcnt vmcnt(7)
	v_mov_b32_e32 v11, v224
	s_waitcnt lgkmcnt(0)
	s_barrier
	s_cselect_b32 s99, 1, 0
	v_readfirstlane_b32 s98, v224
	s_lshr_b32 s98, s98, 8
	s_cbranch_scc0 .Lgp_skip1
	s_setprio 1
.Lgp_skip1:
	s_cmp_lg_u32 s99, 0
	s_and_b64 vcc, exec, s[12:13]
	v_readfirstlane_b32 s3, v11
	s_cbranch_vccz .Lprep_in_odd
	v_lshlrev_b32_e32 v0, 4, v11
	v_add_u32_e32 v1, 0x2000, v0
	v_ashrrev_i32_e32 v2, 31, v1
	v_lshrrev_b32_e32 v2, 22, v2
	v_add_u32_e32 v2, v1, v2
	v_ashrrev_i32_e32 v8, 10, v2
	v_mul_i32_i24_e32 v2, 0x400, v8
	v_sub_u32_e32 v1, v1, v2
	v_lshrrev_b32_e32 v2, 4, v1
	v_bitop3_b32 v1, v2, v1, 32 bitop3:0x6c
	v_ashrrev_i32_e32 v2, 31, v1
	v_lshrrev_b32_e32 v2, 26, v2
	v_add_u32_e32 v2, v1, v2
	v_lshlrev_b32_e32 v3, 3, v8
	v_ashrrev_i32_e32 v9, 6, v2
	v_and_b32_e32 v3, -16, v3
	v_add_u32_e32 v3, v9, v3
	s_waitcnt vmcnt(2)
	v_and_b32_e32 v4, 3, v9
	s_mov_b32 s1, 0x1fffe0
	v_lshrrev_b32_e32 v5, 2, v3
	v_lshlrev_b32_e32 v6, 1, v3
	v_and_b32_e32 v2, 0xc0, v2
	v_and_or_b32 v4, v3, s1, v4
	v_and_b32_e32 v5, 4, v5
	v_and_b32_e32 v6, 24, v6
	v_sub_u32_e32 v1, v1, v2
	v_mov_b32_e32 v2, 1
	v_or3_b32 v4, v4, v5, v6
	v_lshlrev_b32_e32 v5, 5, v8
	v_ashrrev_i16_sdwa v1, v2, sext(v1) dst_sel:DWORD dst_unused:UNUSED_PAD src0_sel:DWORD src1_sel:BYTE_0
	v_and_b32_e32 v5, 32, v5
	v_bfe_i32 v10, v1, 0, 16
	v_add_lshl_u32 v1, v5, v10, 1
	v_lshl_add_u32 v144, v4, 11, v1
	v_lshl_add_u32 v146, v3, 11, v1
	v_bfe_i32 v1, v11, 27, 1
	v_lshrrev_b32_e32 v1, 22, v1
	v_add_u32_e32 v1, v0, v1
	v_and_b32_e32 v1, 0xfffffc00, v1
	v_sub_u32_e32 v0, v0, v1
	v_lshrrev_b32_e32 v1, 4, v0
	v_bitop3_b32 v1, v1, v0, 32 bitop3:0x6c
	v_ashrrev_i32_e32 v0, 31, v0
	v_lshrrev_b32_e32 v0, 26, v0
	v_add_u32_e32 v0, v1, v0
	v_ashrrev_i32_e32 v12, 6, v0
	v_ashrrev_i32_e32 v0, 31, v11
	v_lshrrev_b32_e32 v0, 26, v0
	v_add_u32_e32 v0, v11, v0
	v_ashrrev_i32_e32 v13, 6, v0
	s_ashr_i32 s0, s3, 6
	v_lshlrev_b32_e32 v0, 3, v13
	v_readlane_b32 s18, v255, 5
	s_ashr_i32 s5, s3, 8
	s_lshl_b32 s16, s0, 10
	v_and_b32_e32 v0, -16, v0
	v_readlane_b32 s19, v255, 6
	v_add_u32_e32 v0, v12, v0
	v_and_b32_e32 v3, 3, v12
	s_and_b64 s[18:19], s[18:19], exec
	v_and_or_b32 v3, v0, s1, v3
	s_cselect_b32 s1, 25, 24
	v_readlane_b32 s4, v255, 4
	s_mul_i32 s1, s4, s1
	v_readlane_b32 s4, v255, 3
	s_add_i32 s1, s1, s4
	s_ashr_i32 s4, s1, 31
	s_lshr_b32 s4, s4, 27
	s_add_i32 s4, s1, s4
	s_ashr_i32 s17, s4, 5
	s_and_b32 s4, s4, 0xffe0
	s_sub_i32 s1, s1, s4
	s_bfe_i32 s4, s1, 0x80000
	s_bfe_u32 s4, s4, 0x3000c
	s_add_i32 s18, s1, s4
	s_bfe_i32 s4, s18, 0x80000
	s_and_b32 s18, s18, 0xf8
	v_lshrrev_b32_e32 v4, 2, v0
	v_lshlrev_b32_e32 v5, 1, v0
	s_sub_i32 s1, s1, s18
	v_and_b32_e32 v4, 4, v4
	v_and_b32_e32 v5, 24, v5
	s_lshl_b32 s17, s17, 3
	s_sext_i32_i16 s4, s4
	s_sext_i32_i8 s1, s1
	v_or3_b32 v3, v3, v4, v5
	v_mul_i32_i24_e32 v5, 64, v12
	s_lshr_b32 s4, s4, 3
	s_add_i32 s52, s17, s1
	v_sub_u32_e32 v1, v1, v5
	s_ashr_i32 s53, s52, 31
	s_bfe_i64 s[28:29], s[4:5], 0x100000
	v_lshlrev_b32_e32 v4, 5, v13
	v_ashrrev_i16_sdwa v1, v2, sext(v1) dst_sel:DWORD dst_unused:UNUSED_PAD src0_sel:DWORD src1_sel:BYTE_0
	s_lshl_b64 s[18:19], s[52:53], 19
	s_lshl_b64 s[28:29], s[28:29], 19
	v_and_b32_e32 v4, 32, v4
	v_bfe_i32 v14, v1, 0, 16
	s_add_u32 s62, s6, s28
	v_add_lshl_u32 v1, v4, v14, 1
	s_addc_u32 s63, s7, s29
	s_add_i32 s17, s16, 0
	v_lshl_add_u32 v148, v3, 11, v1
	s_add_i32 m0, s17, 0x10000
	v_lshl_add_u32 v150, v0, 11, v1
	global_load_lds_dwordx4 v148, s[62:63]
	s_add_i32 m0, s17, 0x12000
	s_add_u32 s56, s30, s18
	global_load_lds_dwordx4 v144, s[62:63]
	s_addc_u32 s57, s31, s19
	s_mov_b32 m0, s17
	s_add_i32 s19, s17, 0x2000
	global_load_lds_dwordx4 v150, s[56:57]
	s_mov_b32 m0, s19
	s_add_u32 s28, s62, 0x40000
	global_load_lds_dwordx4 v146, s[56:57]
	s_addc_u32 s29, s63, 0
	s_add_i32 m0, s17, 0x14000
	v_mov_b32_e32 v149, 0
	global_load_lds_dwordx4 v148, s[28:29]
	s_add_i32 m0, s17, 0x16000
	s_add_u32 s40, s56, 0x40000
	global_load_lds_dwordx4 v144, s[28:29]
	s_addc_u32 s41, s57, 0
	s_add_i32 s28, s17, 0x4000
	s_mov_b32 m0, s28
	s_add_i32 s29, s17, 0x6000
	global_load_lds_dwordx4 v150, s[40:41]
	s_mov_b32 m0, s29
	v_mov_b32_e32 v145, v149
	global_load_lds_dwordx4 v146, s[40:41]
	v_mov_b32_e32 v151, v149
	v_mov_b32_e32 v147, v149
	s_mov_b32 s35, 0
	v_lshl_add_u64 v[6:7], s[62:63], 0, v[148:149]
	v_lshl_add_u64 v[4:5], s[62:63], 0, v[144:145]
	v_lshl_add_u64 v[0:1], s[56:57], 0, v[150:151]
	s_cmp_lg_u32 s5, 1
	v_lshl_add_u64 v[2:3], s[56:57], 0, v[146:147]
	s_cbranch_scc1 .LBB0_1062
	s_barrier

.LBB0_1071:
	s_setprio 0
	s_waitcnt vmcnt(0)
	s_waitcnt lgkmcnt(0)
	s_barrier
	s_mov_b64 s[0:1], exec
	v_readlane_b32 s4, v254, 9
	v_readlane_b32 s5, v254, 10
	s_and_b64 s[4:5], s[0:1], s[4:5]
	s_xor_b64 s[0:1], s[4:5], s[0:1]
	s_mov_b64 exec, s[4:5]
	s_cbranch_execz .LBB0_1125
	s_add_i32 s3, 0, 0x20000
	v_mov_b32_e32 v0, s3
	s_waitcnt vmcnt(0) expcnt(0) lgkmcnt(0)
	ds_read_b32 v2, v0
	s_add_i32 s3, 0, 0x20004
	v_mov_b32_e32 v0, s3
	ds_read_b32 v0, v0
	s_waitcnt lgkmcnt(1)
	v_cmp_ne_u32_e32 vcc, 0, v2
	s_cbranch_vccnz .LBB0_1088
	s_add_u32 s4, s24, 0xed22200
	s_addc_u32 s5, s25, 0
	s_add_u32 s6, s24, 0xed22400
	s_addc_u32 s7, s25, 0
	s_add_u32 s40, s24, 0xed22500
	s_addc_u32 s41, s25, 0
	s_add_u32 s42, s24, 0xed22600
	s_addc_u32 s43, s25, 0
	s_add_u32 s46, s24, 0xed22700
	s_addc_u32 s47, s25, 0
	s_add_u32 s48, s24, 0xed22800
	s_addc_u32 s49, s25, 0
	s_add_u32 s52, s24, 0xed22900
	s_addc_u32 s53, s25, 0
	s_add_u32 s56, s24, 0xed22a00
	s_addc_u32 s57, s25, 0
	s_add_u32 s62, s24, 0xed22b00
	s_addc_u32 s63, s25, 0
	s_add_u32 s64, s24, 0xed22c00
	s_addc_u32 s65, s25, 0
	s_add_u32 s66, s24, 0xed22d00
	s_addc_u32 s67, s25, 0
	s_add_u32 s68, s24, 0xed22e00
	s_addc_u32 s69, s25, 0
	s_add_u32 s74, s24, 0xed22f00
	s_addc_u32 s75, s25, 0
	s_add_u32 s80, s24, 0xed23000
	s_addc_u32 s81, s25, 0
	s_add_u32 s82, s24, 0xed23100
	s_addc_u32 s83, s25, 0
	s_add_u32 s84, s24, 0xed23200
	v_readlane_b32 s3, v254, 8
	s_addc_u32 s85, s25, 0
	s_mul_i32 s3, s27, s3
	s_add_u32 s86, s24, 0xed23300
	s_mul_i32 s3, s3, s26
	s_addc_u32 s87, s25, 0
	s_mov_b32 s19, 1
	v_mov_b32_e32 v16, 0
	s_branch .LBB0_1076

.LBB0_1254:
	s_or_b64 exec, exec, s[0:1]
	v_readlane_b32 s0, v255, 0
	v_mov_b32_e32 v8, v224
	v_readlane_b32 s1, v255, 1
	s_waitcnt lgkmcnt(0)
	s_barrier
	s_cselect_b32 s99, 1, 0
	v_readfirstlane_b32 s98, v224
	s_lshr_b32 s98, s98, 8
	s_cbranch_scc0 .Lgp_skip2
	s_setprio 1
.Lgp_skip2:
	s_cmp_lg_u32 s99, 0
	s_and_b64 vcc, exec, s[0:1]
	v_readfirstlane_b32 s16, v8
	s_cbranch_vccz .LBB0_1256
	v_readlane_b32 s0, v255, 5
	v_readlane_b32 s1, v255, 6
	s_movk_i32 s3, 0x61
	s_and_b64 s[0:1], s[0:1], exec
	s_cselect_b32 s0, s3, 0x60
	v_readlane_b32 s1, v255, 4
	s_mul_i32 s0, s1, s0
	v_readlane_b32 s1, v255, 3
	s_add_i32 s0, s0, s1
	s_ashr_i32 s1, s0, 31
	s_lshr_b32 s1, s1, 25
	s_add_i32 s1, s0, s1
	s_ashr_i32 s3, s1, 7
	s_and_b32 s1, s1, 0xff80
	s_sub_i32 s0, s0, s1
	s_bfe_i32 s1, s0, 0x80000
	s_bfe_u32 s1, s1, 0x3000c
	s_add_i32 s1, s0, s1
	s_bfe_i32 s4, s1, 0x80000
	s_and_b32 s1, s1, 0xf8
	s_sub_i32 s0, s0, s1
	s_lshl_b32 s3, s3, 3
	s_sext_i32_i16 s4, s4
	s_sext_i32_i8 s0, s0
	s_add_i32 s6, s3, s0
	s_ashr_i32 s54, s4, 3

.LBB0_1300:
	s_setprio 0
	s_waitcnt vmcnt(0)
	s_waitcnt vmcnt(0) lgkmcnt(0)
	s_barrier
	s_mov_b64 s[0:1], exec
	v_readlane_b32 s4, v254, 9
	v_readlane_b32 s5, v254, 10
	s_and_b64 s[4:5], s[0:1], s[4:5]
	s_xor_b64 s[0:1], s[4:5], s[0:1]
	s_mov_b64 exec, s[4:5]
	s_cbranch_execz .LBB0_1353
	s_add_i32 s3, 0, 0x20000
	v_mov_b32_e32 v0, s3
	s_waitcnt vmcnt(0) expcnt(0) lgkmcnt(0)
	ds_read_b32 v2, v0
	s_add_i32 s3, 0, 0x20004
	v_mov_b32_e32 v0, s3
	ds_read_b32 v0, v0
	s_waitcnt lgkmcnt(1)
	v_cmp_ne_u32_e32 vcc, 0, v2
	s_cbranch_vccnz .LBB0_1316
	s_add_u32 s4, s24, 0xed22200
	s_addc_u32 s5, s25, 0
	s_add_u32 s6, s24, 0xed22400
	s_addc_u32 s7, s25, 0
	s_add_u32 s14, s24, 0xed22500
	s_addc_u32 s15, s25, 0
	s_add_u32 s36, s24, 0xed22600
	s_addc_u32 s37, s25, 0
	s_add_u32 s38, s24, 0xed22700
	s_addc_u32 s39, s25, 0
	s_add_u32 s40, s24, 0xed22800
	s_addc_u32 s41, s25, 0
	s_add_u32 s42, s24, 0xed22900
	s_addc_u32 s43, s25, 0
	s_add_u32 s46, s24, 0xed22a00
	s_addc_u32 s47, s25, 0
	s_add_u32 s48, s24, 0xed22b00
	s_addc_u32 s49, s25, 0
	s_add_u32 s50, s24, 0xed22c00
	s_addc_u32 s51, s25, 0
	s_add_u32 s52, s24, 0xed22d00
	s_addc_u32 s53, s25, 0
	s_add_u32 s54, s24, 0xed22e00
	s_addc_u32 s55, s25, 0
	s_add_u32 s56, s24, 0xed22f00
	s_addc_u32 s57, s25, 0
	s_add_u32 s62, s24, 0xed23000
	s_addc_u32 s63, s25, 0
	s_add_u32 s64, s24, 0xed23100
	s_addc_u32 s65, s25, 0
	s_add_u32 s66, s24, 0xed23200
	v_readlane_b32 s3, v254, 8
	s_addc_u32 s67, s25, 0
	s_mul_i32 s3, s27, s3
	s_add_u32 s68, s24, 0xed23300
	s_mul_i32 s3, s3, s26
	s_addc_u32 s69, s25, 0
	s_mov_b32 s19, 1
	v_mov_b32_e32 v16, 0
	s_branch .LBB0_1304

.LBB0_1492:
	s_or_b64 exec, exec, s[0:1]
	s_add_u32 s4, s24, 0xbd22000
	s_waitcnt vmcnt(3)
	v_mov_b32_e32 v9, v224
	s_waitcnt lgkmcnt(0)
	s_barrier
	s_cselect_b32 s99, 1, 0
	v_readfirstlane_b32 s98, v224
	s_lshr_b32 s98, s98, 8
	s_cbranch_scc0 .Lgp_skip3
	s_setprio 1
.Lgp_skip3:
	s_cmp_lg_u32 s99, 0
	s_addc_u32 s5, s25, 0
	s_andn2_b64 vcc, exec, s[12:13]
	v_readfirstlane_b32 s3, v9
	s_cbranch_vccnz .LBB0_1504
	v_lshlrev_b32_e32 v0, 4, v9
	v_add_u32_e32 v1, 0x2000, v0
	v_ashrrev_i32_e32 v2, 31, v1
	v_lshrrev_b32_e32 v2, 22, v2
	v_add_u32_e32 v2, v1, v2
	v_ashrrev_i32_e32 v8, 10, v2
	v_mul_i32_i24_e32 v2, 0x400, v8
	v_sub_u32_e32 v1, v1, v2
	v_lshrrev_b32_e32 v2, 4, v1
	v_bitop3_b32 v1, v2, v1, 32 bitop3:0x6c
	v_ashrrev_i32_e32 v2, 31, v1
	v_lshrrev_b32_e32 v2, 26, v2
	v_add_u32_e32 v2, v1, v2
	v_lshlrev_b32_e32 v3, 3, v8
	v_ashrrev_i32_e32 v10, 6, v2
	v_and_b32_e32 v3, -16, v3
	v_add_u32_e32 v3, v10, v3
	s_waitcnt vmcnt(2)
	v_and_b32_e32 v4, 3, v10
	s_mov_b32 s0, 0x1fffe0
	v_lshrrev_b32_e32 v5, 2, v3
	v_lshlrev_b32_e32 v6, 1, v3
	v_and_b32_e32 v2, 0xc0, v2
	v_and_or_b32 v4, v3, s0, v4
	v_and_b32_e32 v5, 4, v5
	v_and_b32_e32 v6, 24, v6
	v_sub_u32_e32 v1, v1, v2
	v_mov_b32_e32 v2, 1
	v_or3_b32 v4, v4, v5, v6
	v_lshlrev_b32_e32 v5, 5, v8
	v_ashrrev_i16_sdwa v1, v2, sext(v1) dst_sel:DWORD dst_unused:UNUSED_PAD src0_sel:DWORD src1_sel:BYTE_0
	v_and_b32_e32 v5, 32, v5
	v_bfe_i32 v11, v1, 0, 16
	v_add_lshl_u32 v1, v5, v11, 1
	v_lshl_add_u32 v144, v4, 11, v1
	v_lshl_add_u32 v146, v3, 11, v1
	v_bfe_i32 v1, v9, 27, 1
	v_lshrrev_b32_e32 v1, 22, v1
	v_add_u32_e32 v1, v0, v1
	v_and_b32_e32 v1, 0xfffffc00, v1
	v_sub_u32_e32 v0, v0, v1
	v_lshrrev_b32_e32 v1, 4, v0
	v_bitop3_b32 v1, v1, v0, 32 bitop3:0x6c
	v_ashrrev_i32_e32 v0, 31, v0
	v_lshrrev_b32_e32 v0, 26, v0
	v_add_u32_e32 v0, v1, v0
	v_ashrrev_i32_e32 v12, 6, v0
	v_ashrrev_i32_e32 v0, 31, v9
	v_lshrrev_b32_e32 v0, 26, v0
	v_add_u32_e32 v0, v9, v0
	v_ashrrev_i32_e32 v13, 6, v0
	s_ashr_i32 s12, s3, 6
	v_lshlrev_b32_e32 v0, 3, v13
	v_readlane_b32 s6, v255, 5
	s_ashr_i32 s1, s3, 8
	s_lshl_b32 s16, s12, 10
	v_and_b32_e32 v0, -16, v0
	v_readlane_b32 s7, v255, 6
	v_add_u32_e32 v0, v12, v0
	v_and_b32_e32 v3, 3, v12
	s_and_b64 s[6:7], s[6:7], exec
	v_and_or_b32 v3, v0, s0, v3
	s_cselect_b32 s0, 25, 24
	v_readlane_b32 s6, v255, 4
	s_mul_i32 s0, s6, s0
	v_readlane_b32 s6, v255, 3
	s_add_i32 s0, s0, s6
	s_ashr_i32 s6, s0, 31
	s_lshr_b32 s6, s6, 27
	s_add_i32 s6, s0, s6
	s_ashr_i32 s7, s6, 5
	s_and_b32 s6, s6, 0xffe0
	s_sub_i32 s6, s0, s6
	s_bfe_i32 s0, s6, 0x80000
	s_bfe_u32 s0, s0, 0x3000c
	s_add_i32 s13, s6, s0
	s_bfe_i32 s0, s13, 0x80000
	s_and_b32 s13, s13, 0xf8
	v_lshrrev_b32_e32 v4, 2, v0
	v_lshlrev_b32_e32 v5, 1, v0
	s_sub_i32 s6, s6, s13
	v_and_b32_e32 v4, 4, v4
	v_and_b32_e32 v5, 24, v5
	s_lshl_b32 s7, s7, 3
	s_sext_i32_i16 s0, s0
	s_sext_i32_i8 s6, s6
	v_or3_b32 v3, v3, v4, v5
	v_mul_i32_i24_e32 v5, 64, v12
	s_lshr_b32 s0, s0, 3
	s_add_i32 s50, s7, s6
	v_sub_u32_e32 v1, v1, v5
	s_ashr_i32 s51, s50, 31
	s_bfe_i64 s[14:15], s[0:1], 0x100000
	v_lshlrev_b32_e32 v4, 5, v13
	v_ashrrev_i16_sdwa v1, v2, sext(v1) dst_sel:DWORD dst_unused:UNUSED_PAD src0_sel:DWORD src1_sel:BYTE_0
	s_lshl_b64 s[6:7], s[50:51], 19
	s_lshl_b64 s[14:15], s[14:15], 19
	v_and_b32_e32 v4, 32, v4
	v_bfe_i32 v14, v1, 0, 16
	s_add_u32 s54, s8, s14
	v_add_lshl_u32 v1, v4, v14, 1
	s_addc_u32 s55, s9, s15
	s_add_i32 s17, s16, 0
	v_lshl_add_u32 v148, v3, 11, v1
	s_add_i32 m0, s17, 0x10000
	v_lshl_add_u32 v150, v0, 11, v1
	global_load_lds_dwordx4 v148, s[54:55]
	s_add_i32 m0, s17, 0x12000
	s_add_u32 s52, s30, s6
	global_load_lds_dwordx4 v144, s[54:55]
	s_addc_u32 s53, s31, s7
	s_mov_b32 m0, s17
	s_add_i32 s19, s17, 0x2000
	global_load_lds_dwordx4 v150, s[52:53]
	s_mov_b32 m0, s19
	s_add_u32 s6, s54, 0x40000
	global_load_lds_dwordx4 v146, s[52:53]
	s_addc_u32 s7, s55, 0
	s_add_i32 m0, s17, 0x14000
	v_mov_b32_e32 v149, 0
	global_load_lds_dwordx4 v148, s[6:7]
	s_add_i32 m0, s17, 0x16000
	v_mov_b32_e32 v145, v149
	global_load_lds_dwordx4 v144, s[6:7]
	s_add_u32 s6, s52, 0x40000
	s_addc_u32 s7, s53, 0
	s_add_i32 s28, s17, 0x4000
	s_mov_b32 m0, s28
	s_add_i32 s29, s17, 0x6000
	global_load_lds_dwordx4 v150, s[6:7]
	s_mov_b32 m0, s29
	v_mov_b32_e32 v151, v149
	global_load_lds_dwordx4 v146, s[6:7]
	v_mov_b32_e32 v147, v149
	s_mov_b32 s35, 0
	v_lshl_add_u64 v[6:7], s[54:55], 0, v[148:149]
	v_lshl_add_u64 v[4:5], s[54:55], 0, v[144:145]
	v_lshl_add_u64 v[2:3], s[52:53], 0, v[150:151]
	v_lshl_add_u64 v[0:1], s[52:53], 0, v[146:147]
	s_cmp_lg_u32 s1, 1
	s_mov_b64 s[6:7], 0x40000
	s_cbranch_scc1 .LBB0_1495
	s_barrier

.LBB0_1504:
	s_setprio 0
	s_waitcnt vmcnt(0)
	s_waitcnt lgkmcnt(0)
	s_barrier
	s_mov_b64 s[0:1], exec
	v_readlane_b32 s2, v254, 9
	v_readlane_b32 s3, v254, 10
	s_and_b64 s[2:3], s[0:1], s[2:3]
	s_mov_b64 exec, s[2:3]
	s_cbranch_execz .LBB0_1556
	s_add_i32 s2, 0, 0x20000
	v_mov_b32_e32 v0, s2
	s_waitcnt vmcnt(0) expcnt(0) lgkmcnt(0)
	ds_read_b32 v2, v0
	s_add_i32 s2, 0, 0x20004
	v_mov_b32_e32 v0, s2
	ds_read_b32 v0, v0
	s_waitcnt lgkmcnt(1)
	v_cmp_ne_u32_e32 vcc, 0, v2
	s_cbranch_vccnz .LBB0_1520
	v_readlane_b32 s2, v254, 8
	s_mul_i32 s19, s27, s2
	s_add_u32 s2, s24, 0xed22200
	s_addc_u32 s3, s25, 0
	s_add_u32 s6, s24, 0xed22400
	s_addc_u32 s7, s25, 0
	s_add_u32 s8, s24, 0xed22500
	s_addc_u32 s9, s25, 0
	s_add_u32 s12, s24, 0xed22600
	s_addc_u32 s13, s25, 0
	s_add_u32 s14, s24, 0xed22700
	s_addc_u32 s15, s25, 0
	s_add_u32 s16, s24, 0xed22800
	s_addc_u32 s17, s25, 0
	s_add_u32 s30, s24, 0xed22900
	s_addc_u32 s31, s25, 0
	s_add_u32 s36, s24, 0xed22a00
	s_addc_u32 s37, s25, 0
	s_add_u32 s38, s24, 0xed22b00
	s_addc_u32 s39, s25, 0
	s_add_u32 s40, s24, 0xed22c00
	s_addc_u32 s41, s25, 0
	s_add_u32 s42, s24, 0xed22d00
	s_addc_u32 s43, s25, 0
	s_add_u32 s44, s24, 0xed22e00
	s_addc_u32 s45, s25, 0
	s_add_u32 s46, s24, 0xed22f00
	s_addc_u32 s47, s25, 0
	s_add_u32 s48, s24, 0xed23000
	s_addc_u32 s49, s25, 0
	s_add_u32 s50, s24, 0xed23100
	s_addc_u32 s51, s25, 0
	s_add_u32 s52, s24, 0xed23200
	s_addc_u32 s53, s25, 0
	s_add_u32 s54, s24, 0xed23300
	s_mul_i32 s19, s19, s26
	s_addc_u32 s55, s25, 0
	s_mov_b32 s27, 1
	v_mov_b32_e32 v16, 0
	s_branch .LBB0_1508
